# merge: first-tile loads of the Y@WB gemm issued at block top into idle prefetch regs v66-97 so the gate sigmoid/pack VALU overlaps their latency (on v60)
# speedup vs baseline: 1.0078x; 1.0007x over previous
; DI unsigned pack2(float a, float b) { f2_t v = {a, b}; return __builtin_bit_cast(unsigned, __builtin_convertvector(v, bf2_t)); }
; DI float sigmoidf_(float x) { return __builtin_amdgcn_rcpf(1.f + __expf(-x)); }
; template <int NI, int NB, bool SWAP = false>
; DI void gemm_main(f32x16 (&acc0)[2][NI], f32x16 (&acc1)[2][NI], const bf16_t* __restrict__ A, int lda,
;                   const bf16_t* __restrict__ B0, const bf16_t* __restrict__ B1, int ldb, int K, char* lds) {
;     ...
; #pragma unroll
;   for (int i = 0; i < 4; ++i) ra[i] = *(const u32x4*)(Ab + (aoff + astep * i));
; #pragma unroll
;   for (int i = 0; i < 2 * NI; ++i) {
;     rb0[i] = *(const u32x4*)(B0b + (boff + bstep * i));
;     if (NB == 2) rb1[i] = *(const u32x4*)(B1b + (boff + bstep * i));
;   }
; DI void phase_merge(const bf16_t* __restrict__ Np, const bf16_t* __restrict__ Y, const bf16_t* __restrict__ WG,
;                             const bf16_t* __restrict__ WB, bf16_t* __restrict__ M, char* lds) {
;     ...
;         gemm_main<2, 1, true>(ag, ag, Np + (size_t)mt * 128 * 1024, 1024, WG + (size_t)n * 1048576 + (size_t)nt * 128 * 1024, nullptr, 1024, 1024, lds);
; #pragma unroll
;         for (int mi = 0; mi < 2; ++mi)
; #pragma unroll
;           for (int ni = 0; ni < 2; ++ni)
; #pragma unroll
;             for (int r = 0; r < 8; ++r) sg[mi][ni][r] = pack2(sigmoidf_(ag[mi][ni][2 * r]), sigmoidf_(ag[mi][ni][2 * r + 1]));
;       }
;       f32x16 ab[2][2];
;       zero_acc<2>(ab);
;       gemm_main<2, 1, true>(ab, ab, Y + (size_t)mt * 128 * 1024 + n * 256, 1024, WB + (size_t)n * 262144 + (size_t)nt * 128 * 256, nullptr, 256, 256, lds);
.LBB0_960:
	s_lshl_b32 s6, s28, 9
	s_add_u32 s34, s47, s6
	s_addc_u32 s35, s48, 0
	s_lshl_b64 s[6:7], s[28:29], 19
	s_add_u32 s6, s49, s6
	s_addc_u32 s7, s50, s7
	v_lshlrev_b32_e32 v249, 4, v210
	v_ashrrev_i32_e32 v250, 3, v210
	v_and_b32_e32 v251, 0x70, v249
	v_lshl_or_b32 v200, v250, 11, v251
	v_lshl_or_b32 v201, v250, 9, v251
	v_add_u32_e32 v248, 0x10000, v200
	v_add_u32_e32 v249, 0x20000, v200
	v_add_u32_e32 v250, 0x30000, v200
	v_add_u32_e32 v251, 0x4000, v201
	v_add_u32_e32 v199, 0x8000, v201
	v_add_u32_e32 v245, 0xc000, v201
	global_load_dwordx4 v[66:69], v200, s[34:35]
	global_load_dwordx4 v[70:73], v248, s[34:35]
	global_load_dwordx4 v[74:77], v249, s[34:35]
	global_load_dwordx4 v[78:81], v250, s[34:35]
	global_load_dwordx4 v[82:85], v201, s[6:7]
	global_load_dwordx4 v[86:89], v251, s[6:7]
	global_load_dwordx4 v[90:93], v199, s[6:7]
	global_load_dwordx4 v[94:97], v245, s[6:7]
	s_nop 3
	v_mul_f32_e32 v34, 0xbfb8aa3b, v34
	v_mul_f32_e32 v35, 0xbfb8aa3b, v35
	s_nop 1
	v_mul_f32_e32 v2, 0xbfb8aa3b, v2
	v_mul_f32_e32 v3, 0xbfb8aa3b, v3
	v_exp_f32_e32 v34, v34
	v_exp_f32_e32 v35, v35
	v_exp_f32_e32 v2, v2
	v_exp_f32_e32 v3, v3
	v_add_f32_e32 v34, 1.0, v34
	v_add_f32_e32 v35, 1.0, v35
	v_add_f32_e32 v2, 1.0, v2
	v_add_f32_e32 v3, 1.0, v3
	v_rcp_f32_e32 v34, v34
	v_rcp_f32_e32 v35, v35
	v_rcp_f32_e32 v2, v2
	v_rcp_f32_e32 v3, v3
	v_mul_f32_e32 v18, 0xbfb8aa3b, v18
	v_mul_f32_e32 v19, 0xbfb8aa3b, v19
	v_exp_f32_e32 v18, v18
	v_exp_f32_e32 v19, v19
	v_cvt_pk_bf16_f32 v175, v34, v35
	v_mul_f32_e32 v34, 0xbfb8aa3b, v36
	v_mul_f32_e32 v35, 0xbfb8aa3b, v37
	v_cvt_pk_bf16_f32 v191, v2, v3
	v_mul_f32_e32 v2, 0xbfb8aa3b, v4
	v_mul_f32_e32 v3, 0xbfb8aa3b, v5
	v_exp_f32_e32 v34, v34
	v_exp_f32_e32 v35, v35
	v_exp_f32_e32 v2, v2
	v_exp_f32_e32 v3, v3
	v_add_f32_e32 v18, 1.0, v18
	v_add_f32_e32 v19, 1.0, v19
	v_rcp_f32_e32 v18, v18
	v_rcp_f32_e32 v19, v19
	v_add_f32_e32 v34, 1.0, v34
	v_add_f32_e32 v35, 1.0, v35
	v_add_f32_e32 v2, 1.0, v2
	v_add_f32_e32 v3, 1.0, v3
	v_rcp_f32_e32 v34, v34
	v_rcp_f32_e32 v35, v35
	v_rcp_f32_e32 v2, v2
	v_rcp_f32_e32 v3, v3
	v_cvt_pk_bf16_f32 v183, v18, v19
	v_mul_f32_e32 v18, 0xbfb8aa3b, v20
	v_mul_f32_e32 v19, 0xbfb8aa3b, v21
	v_exp_f32_e32 v18, v18
	v_exp_f32_e32 v19, v19
	v_cvt_pk_bf16_f32 v176, v34, v35
	v_mul_f32_e32 v34, 0xbfb8aa3b, v38
	v_mul_f32_e32 v35, 0xbfb8aa3b, v39
	v_cvt_pk_bf16_f32 v192, v2, v3
	v_mul_f32_e32 v2, 0xbfb8aa3b, v6
	v_mul_f32_e32 v3, 0xbfb8aa3b, v7
	v_exp_f32_e32 v34, v34
	v_exp_f32_e32 v35, v35
	v_exp_f32_e32 v2, v2
	v_exp_f32_e32 v3, v3
	v_add_f32_e32 v18, 1.0, v18
	v_add_f32_e32 v19, 1.0, v19
	v_rcp_f32_e32 v18, v18
	v_rcp_f32_e32 v19, v19
	v_add_f32_e32 v34, 1.0, v34
	v_add_f32_e32 v35, 1.0, v35
	v_add_f32_e32 v2, 1.0, v2
	v_add_f32_e32 v3, 1.0, v3
	v_rcp_f32_e32 v34, v34
	v_rcp_f32_e32 v35, v35
	v_rcp_f32_e32 v2, v2
	v_rcp_f32_e32 v3, v3
	v_cvt_pk_bf16_f32 v184, v18, v19
	v_mul_f32_e32 v18, 0xbfb8aa3b, v22
	v_mul_f32_e32 v19, 0xbfb8aa3b, v23
	v_exp_f32_e32 v18, v18
	v_exp_f32_e32 v19, v19
	v_cvt_pk_bf16_f32 v177, v34, v35
	v_mul_f32_e32 v34, 0xbfb8aa3b, v40
	v_mul_f32_e32 v35, 0xbfb8aa3b, v41
	v_cvt_pk_bf16_f32 v193, v2, v3
	v_mul_f32_e32 v2, 0xbfb8aa3b, v8
	v_mul_f32_e32 v3, 0xbfb8aa3b, v9
	v_exp_f32_e32 v34, v34
	v_exp_f32_e32 v35, v35
	v_exp_f32_e32 v2, v2
	v_exp_f32_e32 v3, v3
	v_add_f32_e32 v18, 1.0, v18
	v_add_f32_e32 v19, 1.0, v19
	v_rcp_f32_e32 v18, v18
	v_rcp_f32_e32 v19, v19
	v_add_f32_e32 v34, 1.0, v34
	v_add_f32_e32 v35, 1.0, v35
	v_add_f32_e32 v2, 1.0, v2
	v_add_f32_e32 v3, 1.0, v3
	v_rcp_f32_e32 v34, v34
	v_rcp_f32_e32 v35, v35
	v_rcp_f32_e32 v2, v2
	v_rcp_f32_e32 v3, v3
	v_cvt_pk_bf16_f32 v185, v18, v19
	v_mul_f32_e32 v18, 0xbfb8aa3b, v24
	v_mul_f32_e32 v19, 0xbfb8aa3b, v25
	v_exp_f32_e32 v18, v18
	v_exp_f32_e32 v19, v19
	v_cvt_pk_bf16_f32 v178, v34, v35
	v_mul_f32_e32 v34, 0xbfb8aa3b, v42
	v_mul_f32_e32 v35, 0xbfb8aa3b, v43
	v_cvt_pk_bf16_f32 v194, v2, v3
	v_mul_f32_e32 v2, 0xbfb8aa3b, v10
	v_mul_f32_e32 v3, 0xbfb8aa3b, v11
	v_exp_f32_e32 v34, v34
	v_exp_f32_e32 v35, v35
	v_exp_f32_e32 v2, v2
	v_exp_f32_e32 v3, v3
	v_add_f32_e32 v18, 1.0, v18
	v_add_f32_e32 v19, 1.0, v19
	v_rcp_f32_e32 v18, v18
	v_rcp_f32_e32 v19, v19
	v_add_f32_e32 v34, 1.0, v34
	v_add_f32_e32 v35, 1.0, v35
	v_add_f32_e32 v2, 1.0, v2
	v_add_f32_e32 v3, 1.0, v3
	v_rcp_f32_e32 v34, v34
	v_rcp_f32_e32 v35, v35
	v_rcp_f32_e32 v2, v2
	v_rcp_f32_e32 v3, v3
	v_cvt_pk_bf16_f32 v186, v18, v19
	v_mul_f32_e32 v18, 0xbfb8aa3b, v26
	v_mul_f32_e32 v19, 0xbfb8aa3b, v27
	v_exp_f32_e32 v18, v18
	v_exp_f32_e32 v19, v19
	v_cvt_pk_bf16_f32 v179, v34, v35
	v_mul_f32_e32 v34, 0xbfb8aa3b, v44
	v_mul_f32_e32 v35, 0xbfb8aa3b, v45
	v_cvt_pk_bf16_f32 v195, v2, v3
	v_mul_f32_e32 v2, 0xbfb8aa3b, v12
	v_mul_f32_e32 v3, 0xbfb8aa3b, v13
	v_exp_f32_e32 v34, v34
	v_exp_f32_e32 v35, v35
	v_exp_f32_e32 v2, v2
	v_exp_f32_e32 v3, v3
	v_add_f32_e32 v18, 1.0, v18
	v_add_f32_e32 v19, 1.0, v19
	v_rcp_f32_e32 v18, v18
	v_rcp_f32_e32 v19, v19
	v_add_f32_e32 v34, 1.0, v34
	v_add_f32_e32 v35, 1.0, v35
	v_add_f32_e32 v2, 1.0, v2
	v_add_f32_e32 v3, 1.0, v3
	v_rcp_f32_e32 v34, v34
	v_rcp_f32_e32 v35, v35
	v_rcp_f32_e32 v2, v2
	v_rcp_f32_e32 v3, v3
	v_cvt_pk_bf16_f32 v187, v18, v19
	v_mul_f32_e32 v18, 0xbfb8aa3b, v28
	v_mul_f32_e32 v19, 0xbfb8aa3b, v29
	v_exp_f32_e32 v18, v18
	v_exp_f32_e32 v19, v19
	v_cvt_pk_bf16_f32 v180, v34, v35
	v_mul_f32_e32 v34, 0xbfb8aa3b, v46
	v_mul_f32_e32 v35, 0xbfb8aa3b, v47
	v_cvt_pk_bf16_f32 v196, v2, v3
	v_mul_f32_e32 v2, 0xbfb8aa3b, v14
	v_mul_f32_e32 v3, 0xbfb8aa3b, v15
	v_exp_f32_e32 v34, v34
	v_exp_f32_e32 v35, v35
	v_exp_f32_e32 v2, v2
	v_exp_f32_e32 v3, v3
	v_add_f32_e32 v18, 1.0, v18
	v_add_f32_e32 v19, 1.0, v19
; DI unsigned pack2(float a, float b) { f2_t v = {a, b}; return __builtin_bit_cast(unsigned, __builtin_convertvector(v, bf2_t)); }
; DI float sigmoidf_(float x) { return __builtin_amdgcn_rcpf(1.f + __expf(-x)); }
; template <int NI, int NB, bool SWAP = false>
; DI void gemm_main(f32x16 (&acc0)[2][NI], f32x16 (&acc1)[2][NI], const bf16_t* __restrict__ A, int lda,
;                   const bf16_t* __restrict__ B0, const bf16_t* __restrict__ B1, int ldb, int K, char* lds) {
;     ...
;   for (int i = 0; i < 4; ++i) ra[i] = *(const u32x4*)(Ab + (aoff + astep * i));
; #pragma unroll
;   for (int i = 0; i < 2 * NI; ++i) {
;     rb0[i] = *(const u32x4*)(B0b + (boff + bstep * i));
;     if (NB == 2) rb1[i] = *(const u32x4*)(B1b + (boff + bstep * i));
;   }
;   for (int k0 = 0; k0 < K; k0 += 64) {
;     __syncthreads();
; #pragma unroll
;     for (int i = 0; i < 4; ++i) *(u32x4*)(As + (lr + 32 * i) * 72 + lc) = ra[i];
; #pragma unroll
;     for (int i = 0; i < 2 * NI; ++i) {
;       *(u32x4*)(B0s + (lr + 32 * i) * 72 + lc) = rb0[i];
;       if (NB == 2) *(u32x4*)(B1s + (lr + 32 * i) * 72 + lc) = rb1[i];
;     }
;     if (k0 + 64 < K) {
;       const unsigned kb = (unsigned)(k0 + 64) * 2u;
; #pragma unroll
;       for (int i = 0; i < 4; ++i) ra[i] = *(const u32x4*)(Ab + (aoff + astep * i + kb));
; #pragma unroll
;       for (int i = 0; i < 2 * NI; ++i) {
;         rb0[i] = *(const u32x4*)(B0b + (boff + bstep * i + kb));
;         if (NB == 2) rb1[i] = *(const u32x4*)(B1b + (boff + bstep * i + kb));
;       }
;     }
;     __syncthreads();
; DI void phase_merge(const bf16_t* __restrict__ Np, const bf16_t* __restrict__ Y, const bf16_t* __restrict__ WG,
;                             const bf16_t* __restrict__ WB, bf16_t* __restrict__ M, char* lds) {
;     ...
;             for (int r = 0; r < 8; ++r) sg[mi][ni][r] = pack2(sigmoidf_(ag[mi][ni][2 * r]), sigmoidf_(ag[mi][ni][2 * r + 1]));
;       }
;       f32x16 ab[2][2];
;       zero_acc<2>(ab);
;       gemm_main<2, 1, true>(ab, ab, Y + (size_t)mt * 128 * 1024 + n * 256, 1024, WB + (size_t)n * 262144 + (size_t)nt * 128 * 256, nullptr, 256, 256, lds);
	v_rcp_f32_e32 v18, v18
	v_rcp_f32_e32 v19, v19
	v_add_f32_e32 v34, 1.0, v34
	v_add_f32_e32 v35, 1.0, v35
	v_add_f32_e32 v2, 1.0, v2
	v_add_f32_e32 v3, 1.0, v3
	v_rcp_f32_e32 v34, v34
	v_rcp_f32_e32 v35, v35
	v_rcp_f32_e32 v2, v2
	v_rcp_f32_e32 v3, v3
	v_cvt_pk_bf16_f32 v188, v18, v19
	v_mul_f32_e32 v18, 0xbfb8aa3b, v30
	v_mul_f32_e32 v19, 0xbfb8aa3b, v31
	v_exp_f32_e32 v18, v18
	v_exp_f32_e32 v19, v19
	v_cvt_pk_bf16_f32 v181, v34, v35
	v_mul_f32_e32 v34, 0xbfb8aa3b, v48
	v_mul_f32_e32 v35, 0xbfb8aa3b, v49
	v_cvt_pk_bf16_f32 v197, v2, v3
	v_mul_f32_e32 v2, 0xbfb8aa3b, v16
	v_mul_f32_e32 v3, 0xbfb8aa3b, v17
	v_exp_f32_e32 v34, v34
	v_exp_f32_e32 v35, v35
	v_exp_f32_e32 v2, v2
	v_exp_f32_e32 v3, v3
	v_add_f32_e32 v18, 1.0, v18
	v_add_f32_e32 v19, 1.0, v19
	v_rcp_f32_e32 v18, v18
	v_rcp_f32_e32 v19, v19
	v_add_f32_e32 v34, 1.0, v34
	v_add_f32_e32 v35, 1.0, v35
	v_add_f32_e32 v2, 1.0, v2
	v_add_f32_e32 v3, 1.0, v3
	v_rcp_f32_e32 v34, v34
	v_rcp_f32_e32 v35, v35
	v_rcp_f32_e32 v2, v2
	v_rcp_f32_e32 v3, v3
	v_cvt_pk_bf16_f32 v189, v18, v19
	v_mul_f32_e32 v18, 0xbfb8aa3b, v32
	v_mul_f32_e32 v19, 0xbfb8aa3b, v33
	v_exp_f32_e32 v18, v18
	v_exp_f32_e32 v19, v19
	v_cvt_pk_bf16_f32 v182, v34, v35
	v_cvt_pk_bf16_f32 v198, v2, v3
	v_mov_b32 v2, 0
	s_lshl_b32 s6, s28, 9
	v_add_u32_e32 v35, v2, v210
	v_lshlrev_b32_e32 v2, 4, v35
	s_add_u32 s34, s47, s6
	v_ashrrev_i32_e32 v36, 3, v35
	v_and_b32_e32 v37, 0x70, v2
	v_add_f32_e32 v18, 1.0, v18
	v_add_f32_e32 v19, 1.0, v19
	s_addc_u32 s35, s48, 0
	v_lshl_or_b32 v200, v36, 11, v37
	v_rcp_f32_e32 v18, v18
	v_rcp_f32_e32 v19, v19
	v_add_u32_e32 v6, 0x10000, v200
	s_lshl_b64 s[6:7], s[28:29], 19
	v_add_u32_e32 v10, 0x20000, v200
	s_add_u32 s6, s49, s6
	v_add_u32_e32 v14, 0x30000, v200
	s_addc_u32 s7, s50, s7
	v_lshl_or_b32 v201, v36, 9, v37
	v_cvt_pk_bf16_f32 v190, v18, v19
	v_add_u32_e32 v22, 0x4000, v201
	v_add_u32_e32 v26, 0x8000, v201
	v_add_u32_e32 v30, 0xc000, v201
	v_mul_lo_u32 v36, v36, s12
	v_add3_u32 v199, 16, v37, v36
	s_barrier
	s_waitcnt vmcnt(7)
	ds_write_b128 v199, v[66:69]
	s_waitcnt vmcnt(6)
	ds_write_b128 v199, v[70:73] offset:4608
	s_waitcnt vmcnt(5)
	ds_write_b128 v199, v[74:77] offset:9216
	s_waitcnt vmcnt(4)
	ds_write_b128 v199, v[78:81] offset:13824
	s_waitcnt vmcnt(3)
	ds_write_b128 v199, v[82:85] offset:18432
	s_waitcnt vmcnt(2)
	ds_write_b128 v199, v[86:89] offset:23040
	s_waitcnt vmcnt(1)
	ds_write_b128 v199, v[90:93] offset:27648
	s_waitcnt vmcnt(0)
	ds_write_b128 v199, v[94:97] offset:32256
	s_waitcnt lgkmcnt(0)
	v_add_u32_e32 v2, 0x10080, v200
	global_load_dwordx4 v[70:73], v2, s[34:35]
	v_add_u32_e32 v2, 0x20080, v200
	global_load_dwordx4 v[74:77], v2, s[34:35]
	v_add_u32_e32 v2, 0x30080, v200
	global_load_dwordx4 v[78:81], v2, s[34:35]
	v_add_u32_e32 v2, 0xc080, v201
	global_load_dwordx4 v[66:69], v200, s[34:35] offset:128
	global_load_dwordx4 v[82:85], v2, s[6:7]
	v_add_u32_e32 v2, 0x8080, v201
	global_load_dwordx4 v[86:89], v2, s[6:7]
	v_add_u32_e32 v2, 0x4080, v201
	v_mul_f32_e32 v50, 0xbfb8aa3b, v50
	v_mul_f32_e32 v51, 0xbfb8aa3b, v51
	global_load_dwordx4 v[90:93], v2, s[6:7]
	global_load_dwordx4 v[94:97], v201, s[6:7] offset:128
	v_exp_f32_e32 v50, v50
	v_exp_f32_e32 v51, v51
	v_and_b32_e32 v34, 31, v35
	v_lshrrev_b32_e32 v38, 1, v35
	v_add_f32_e32 v50, 1.0, v50
	v_add_f32_e32 v51, 1.0, v51
	v_rcp_f32_e32 v50, v50
	v_rcp_f32_e32 v51, v51
	v_and_or_b32 v39, v38, s11, v34
	v_and_b32_e32 v34, 16, v38
	v_add_u32_e32 v34, 16, v34
	v_cvt_pk_bf16_f32 v167, v50, v51
	v_mul_f32_e32 v50, 0xbfb8aa3b, v52
	v_mul_f32_e32 v51, 0xbfb8aa3b, v53
	v_exp_f32_e32 v50, v50
	v_exp_f32_e32 v51, v51
	v_and_b32_e32 v35, 0x5f, v35
	v_mad_u64_u32 v[164:165], s[52:53], v39, s12, v[34:35]
	v_add_f32_e32 v50, 1.0, v50
	v_add_f32_e32 v51, 1.0, v51
	v_rcp_f32_e32 v50, v50
	v_rcp_f32_e32 v51, v51
	v_mad_u32_u24 v165, v35, s12, v34
	s_waitcnt lgkmcnt(0)
	s_barrier
	v_cvt_pk_bf16_f32 v168, v50, v51
	v_mul_f32_e32 v50, 0xbfb8aa3b, v54
	v_mul_f32_e32 v51, 0xbfb8aa3b, v55
	v_exp_f32_e32 v50, v50
	v_exp_f32_e32 v51, v51
	v_add_f32_e32 v50, 1.0, v50
	v_add_f32_e32 v51, 1.0, v51
	v_rcp_f32_e32 v50, v50
	v_rcp_f32_e32 v51, v51
	s_nop 0
	v_cvt_pk_bf16_f32 v169, v50, v51
	v_mul_f32_e32 v50, 0xbfb8aa3b, v56
	v_mul_f32_e32 v51, 0xbfb8aa3b, v57
	v_exp_f32_e32 v50, v50
	v_exp_f32_e32 v51, v51
	v_add_f32_e32 v50, 1.0, v50
	v_add_f32_e32 v51, 1.0, v51
	v_rcp_f32_e32 v50, v50
	v_rcp_f32_e32 v51, v51
	s_nop 0
	v_cvt_pk_bf16_f32 v170, v50, v51
	v_mul_f32_e32 v50, 0xbfb8aa3b, v58
	v_mul_f32_e32 v51, 0xbfb8aa3b, v59
	v_exp_f32_e32 v50, v50
	v_exp_f32_e32 v51, v51
	v_add_f32_e32 v50, 1.0, v50
	v_add_f32_e32 v51, 1.0, v51
	v_rcp_f32_e32 v50, v50
	v_rcp_f32_e32 v51, v51
	s_nop 0
	v_cvt_pk_bf16_f32 v171, v50, v51
	v_mul_f32_e32 v50, 0xbfb8aa3b, v60
	v_mul_f32_e32 v51, 0xbfb8aa3b, v61
	v_exp_f32_e32 v50, v50
	v_exp_f32_e32 v51, v51
	v_add_f32_e32 v50, 1.0, v50
	v_add_f32_e32 v51, 1.0, v51
	v_rcp_f32_e32 v50, v50
	v_rcp_f32_e32 v51, v51
	s_nop 0
	v_cvt_pk_bf16_f32 v172, v50, v51
	v_mul_f32_e32 v50, 0xbfb8aa3b, v62
	v_mul_f32_e32 v51, 0xbfb8aa3b, v63
	v_exp_f32_e32 v50, v50
	v_exp_f32_e32 v51, v51
	v_add_f32_e32 v50, 1.0, v50
	v_add_f32_e32 v51, 1.0, v51
	v_rcp_f32_e32 v50, v50
	v_rcp_f32_e32 v51, v51
	s_nop 0
	v_cvt_pk_bf16_f32 v173, v50, v51
	v_mul_f32_e32 v50, 0xbfb8aa3b, v64
	v_mul_f32_e32 v51, 0xbfb8aa3b, v65
	v_exp_f32_e32 v50, v50
	v_exp_f32_e32 v51, v51
	v_add_f32_e32 v50, 1.0, v50
	v_add_f32_e32 v51, 1.0, v51
	v_rcp_f32_e32 v50, v50
	v_rcp_f32_e32 v51, v51
	s_nop 0
	v_cvt_pk_bf16_f32 v174, v50, v51
	s_setprio 1
	ds_read_b128 v[2:5], v165 offset:18432
	ds_read_b128 v[6:9], v164
	ds_read_b128 v[10:13], v165 offset:23040
	s_waitcnt lgkmcnt(1)
; #define MFMA32(a, b, c) __builtin_amdgcn_mfma_f32_32x32x16_bf16((a), (b), (c), 0, 0, 0)
; template <int NI, int NB, bool SWAP = false>
; DI void gemm_main(f32x16 (&acc0)[2][NI], f32x16 (&acc1)[2][NI], const bf16_t* __restrict__ A, int lda,
;                   const bf16_t* __restrict__ B0, const bf16_t* __restrict__ B1, int ldb, int K, char* lds) {
;     ...
;   for (int k0 = 0; k0 < K; k0 += 64) {
;     __syncthreads();
; #pragma unroll
;     for (int i = 0; i < 4; ++i) *(u32x4*)(As + (lr + 32 * i) * 72 + lc) = ra[i];
; #pragma unroll
;     for (int i = 0; i < 2 * NI; ++i) {
;       *(u32x4*)(B0s + (lr + 32 * i) * 72 + lc) = rb0[i];
;       if (NB == 2) *(u32x4*)(B1s + (lr + 32 * i) * 72 + lc) = rb1[i];
;     }
;     if (k0 + 64 < K) {
;       const unsigned kb = (unsigned)(k0 + 64) * 2u;
; #pragma unroll
;       for (int i = 0; i < 4; ++i) ra[i] = *(const u32x4*)(Ab + (aoff + astep * i + kb));
; #pragma unroll
;       for (int i = 0; i < 2 * NI; ++i) {
;         rb0[i] = *(const u32x4*)(B0b + (boff + bstep * i + kb));
;         if (NB == 2) rb1[i] = *(const u32x4*)(B1b + (boff + bstep * i + kb));
;       }
;     }
;     __syncthreads();
;     __builtin_amdgcn_s_setprio(1);
; #pragma unroll
;     for (int ks = 0; ks < 4; ++ks) {
;       bf16x8 af[2], bf0[NI], bf1[NI];
; #pragma unroll
;       for (int mi = 0; mi < 2; ++mi) af[mi] = *(const bf16x8*)(As + (64 * wm + 32 * mi + l31) * 72 + 16 * ks + 8 * h2);
; #pragma unroll
;       for (int ni = 0; ni < NI; ++ni) {
;         bf0[ni] = *(const bf16x8*)(B0s + (32 * NI * wn + 32 * ni + l31) * 72 + 16 * ks + 8 * h2);
;         if (NB == 2) bf1[ni] = *(const bf16x8*)(B1s + (32 * NI * wn + 32 * ni + l31) * 72 + 16 * ks + 8 * h2);
;       }
; #pragma unroll
;       for (int mi = 0; mi < 2; ++mi)
; #pragma unroll
;         for (int ni = 0; ni < NI; ++ni) {
;           acc0[mi][ni] = SWAP ? MFMA32(bf0[ni], af[mi], acc0[mi][ni]) : MFMA32(af[mi], bf0[ni], acc0[mi][ni]);
;           if (NB == 2) acc1[mi][ni] = SWAP ? MFMA32(bf1[ni], af[mi], acc1[mi][ni]) : MFMA32(af[mi], bf1[ni], acc1[mi][ni]);
;         }
;     }
	v_mfma_f32_32x32x16_bf16 v[50:65], v[2:5], v[6:9], 0
	s_waitcnt lgkmcnt(0)
	v_mfma_f32_32x32x16_bf16 v[34:49], v[10:13], v[6:9], 0
	ds_read_b128 v[6:9], v164 offset:4608
	ds_read_b128 v[202:205], v165 offset:18464
	ds_read_b128 v[206:209], v164 offset:32
	ds_read_b128 v[220:223], v165 offset:23072
	s_waitcnt lgkmcnt(3)
	v_mfma_f32_32x32x16_bf16 v[18:33], v[2:5], v[6:9], 0
	v_mfma_f32_32x32x16_bf16 v[2:17], v[10:13], v[6:9], 0
	s_waitcnt lgkmcnt(1)
	v_mfma_f32_32x32x16_bf16 v[50:65], v[202:205], v[206:209], v[50:65]
	s_waitcnt lgkmcnt(0)
	v_mfma_f32_32x32x16_bf16 v[34:49], v[220:223], v[206:209], v[34:49]
	ds_read_b128 v[206:209], v164 offset:4640
	s_waitcnt lgkmcnt(0)
	v_mfma_f32_32x32x16_bf16 v[18:33], v[202:205], v[206:209], v[18:33]
	v_mfma_f32_32x32x16_bf16 v[2:17], v[220:223], v[206:209], v[2:17]
	ds_read_b128 v[202:205], v165 offset:18496
	ds_read_b128 v[206:209], v164 offset:64
	ds_read_b128 v[220:223], v165 offset:23104
	s_waitcnt lgkmcnt(1)
	v_mfma_f32_32x32x16_bf16 v[50:65], v[202:205], v[206:209], v[50:65]
	s_waitcnt lgkmcnt(0)
	v_mfma_f32_32x32x16_bf16 v[34:49], v[220:223], v[206:209], v[34:49]
	ds_read_b128 v[206:209], v164 offset:4672
	s_waitcnt lgkmcnt(0)
	v_mfma_f32_32x32x16_bf16 v[18:33], v[202:205], v[206:209], v[18:33]
	v_mfma_f32_32x32x16_bf16 v[2:17], v[220:223], v[206:209], v[2:17]
	ds_read_b128 v[202:205], v165 offset:18528
	ds_read_b128 v[206:209], v164 offset:96
	ds_read_b128 v[220:223], v165 offset:23136
	s_waitcnt lgkmcnt(1)
	v_mfma_f32_32x32x16_bf16 v[50:65], v[202:205], v[206:209], v[50:65]
	s_waitcnt lgkmcnt(0)
	v_mfma_f32_32x32x16_bf16 v[34:49], v[220:223], v[206:209], v[34:49]
	ds_read_b128 v[206:209], v164 offset:4704
	s_waitcnt lgkmcnt(0)
	v_mfma_f32_32x32x16_bf16 v[18:33], v[202:205], v[206:209], v[18:33]
	v_mfma_f32_32x32x16_bf16 v[2:17], v[220:223], v[206:209], v[2:17]
	s_setprio 0
	s_barrier
	s_waitcnt vmcnt(4)
	ds_write_b128 v199, v[66:69]
	ds_write_b128 v199, v[70:73] offset:4608
	ds_write_b128 v199, v[74:77] offset:9216
	ds_write_b128 v199, v[78:81] offset:13824
	s_waitcnt vmcnt(0)
	ds_write_b128 v199, v[94:97] offset:18432
	ds_write_b128 v199, v[90:93] offset:23040
	ds_write_b128 v199, v[86:89] offset:27648
	ds_write_b128 v199, v[82:85] offset:32256
	v_add_u32_e32 v70, 0x10100, v200
	v_add_u32_e32 v74, 0x20100, v200
	v_add_u32_e32 v78, 0x30100, v200
	v_add_u32_e32 v82, 0xc100, v201
	v_add_u32_e32 v86, 0x8100, v201
	v_add_u32_e32 v90, 0x4100, v201
	global_load_dwordx4 v[66:69], v200, s[34:35] offset:256
	s_nop 0
	global_load_dwordx4 v[86:89], v86, s[6:7]
	s_nop 0
	global_load_dwordx4 v[70:73], v70, s[34:35]
	s_nop 0
	global_load_dwordx4 v[74:77], v74, s[34:35]
	s_nop 0
	global_load_dwordx4 v[78:81], v78, s[34:35]
	s_nop 0
	global_load_dwordx4 v[82:85], v82, s[6:7]
	s_nop 0
	global_load_dwordx4 v[90:93], v90, s[6:7]
	s_nop 0
	global_load_dwordx4 v[94:97], v201, s[6:7] offset:256
	s_waitcnt lgkmcnt(0)
	s_barrier
	s_setprio 1
	ds_read_b128 v[202:205], v165 offset:18432
	ds_read_b128 v[206:209], v164
	ds_read_b128 v[220:223], v165 offset:23040
	s_waitcnt lgkmcnt(1)
	v_mfma_f32_32x32x16_bf16 v[50:65], v[202:205], v[206:209], v[50:65]
	s_waitcnt lgkmcnt(0)
	v_mfma_f32_32x32x16_bf16 v[34:49], v[220:223], v[206:209], v[34:49]
	ds_read_b128 v[206:209], v164 offset:4608
	s_waitcnt lgkmcnt(0)
	v_mfma_f32_32x32x16_bf16 v[18:33], v[202:205], v[206:209], v[18:33]
	v_mfma_f32_32x32x16_bf16 v[2:17], v[220:223], v[206:209], v[2:17]
	ds_read_b128 v[202:205], v165 offset:18464
	ds_read_b128 v[206:209], v164 offset:32
	ds_read_b128 v[220:223], v165 offset:23072
	s_waitcnt lgkmcnt(1)
	v_mfma_f32_32x32x16_bf16 v[50:65], v[202:205], v[206:209], v[50:65]
	s_waitcnt lgkmcnt(0)
	v_mfma_f32_32x32x16_bf16 v[34:49], v[220:223], v[206:209], v[34:49]
	ds_read_b128 v[206:209], v164 offset:4640
	s_waitcnt lgkmcnt(0)
	v_mfma_f32_32x32x16_bf16 v[18:33], v[202:205], v[206:209], v[18:33]
	v_mfma_f32_32x32x16_bf16 v[2:17], v[220:223], v[206:209], v[2:17]
	ds_read_b128 v[202:205], v165 offset:18496
	ds_read_b128 v[206:209], v164 offset:64
	ds_read_b128 v[220:223], v165 offset:23104
	s_waitcnt lgkmcnt(1)
	v_mfma_f32_32x32x16_bf16 v[50:65], v[202:205], v[206:209], v[50:65]
	s_waitcnt lgkmcnt(0)
	v_mfma_f32_32x32x16_bf16 v[34:49], v[220:223], v[206:209], v[34:49]
	ds_read_b128 v[206:209], v164 offset:4672
	s_waitcnt lgkmcnt(0)
	v_mfma_f32_32x32x16_bf16 v[18:33], v[202:205], v[206:209], v[18:33]
	v_mfma_f32_32x32x16_bf16 v[2:17], v[220:223], v[206:209], v[2:17]
	ds_read_b128 v[202:205], v165 offset:18528
	ds_read_b128 v[206:209], v164 offset:96
	ds_read_b128 v[220:223], v165 offset:23136
	s_waitcnt lgkmcnt(1)
	v_mfma_f32_32x32x16_bf16 v[50:65], v[202:205], v[206:209], v[50:65]
	s_waitcnt lgkmcnt(0)
	v_mfma_f32_32x32x16_bf16 v[34:49], v[220:223], v[206:209], v[34:49]
	ds_read_b128 v[206:209], v164 offset:4704
	s_waitcnt lgkmcnt(0)
	v_mfma_f32_32x32x16_bf16 v[18:33], v[202:205], v[206:209], v[18:33]
	v_mfma_f32_32x32x16_bf16 v[2:17], v[220:223], v[206:209], v[2:17]
	s_setprio 0
	s_barrier
	s_waitcnt vmcnt(7)
	ds_write_b128 v199, v[66:69]
	s_waitcnt vmcnt(5)
	ds_write_b128 v199, v[70:73] offset:4608
	s_waitcnt vmcnt(4)
	ds_write_b128 v199, v[74:77] offset:9216
	s_waitcnt vmcnt(3)
	ds_write_b128 v199, v[78:81] offset:13824
	s_waitcnt vmcnt(0)
	ds_write_b128 v199, v[94:97] offset:18432
	ds_write_b128 v199, v[90:93] offset:23040
	ds_write_b128 v199, v[86:89] offset:27648
	ds_write_b128 v199, v[82:85] offset:32256
	v_add_u32_e32 v70, 0x10180, v200
	v_add_u32_e32 v74, 0x20180, v200
	v_add_u32_e32 v78, 0x30180, v200
	v_add_u32_e32 v82, 0xc180, v201
	v_add_u32_e32 v86, 0x8180, v201
	v_add_u32_e32 v90, 0x4180, v201
	global_load_dwordx4 v[66:69], v200, s[34:35] offset:384
	s_nop 0
	global_load_dwordx4 v[86:89], v86, s[6:7]
	s_nop 0
	global_load_dwordx4 v[70:73], v70, s[34:35]
	s_nop 0
	global_load_dwordx4 v[74:77], v74, s[34:35]
	s_nop 0
	global_load_dwordx4 v[78:81], v78, s[34:35]
	s_nop 0
	global_load_dwordx4 v[82:85], v82, s[6:7]
	s_nop 0
	global_load_dwordx4 v[90:93], v90, s[6:7]
	s_nop 0
	global_load_dwordx4 v[94:97], v201, s[6:7] offset:384
	s_waitcnt lgkmcnt(0)
	s_barrier
; #define MFMA32(a, b, c) __builtin_amdgcn_mfma_f32_32x32x16_bf16((a), (b), (c), 0, 0, 0)
; template <int NI, int NB, bool SWAP = false>
; DI void gemm_main(f32x16 (&acc0)[2][NI], f32x16 (&acc1)[2][NI], const bf16_t* __restrict__ A, int lda,
;                   const bf16_t* __restrict__ B0, const bf16_t* __restrict__ B1, int ldb, int K, char* lds) {
;     ...
;     __syncthreads();
; #pragma unroll
;     for (int i = 0; i < 4; ++i) *(u32x4*)(As + (lr + 32 * i) * 72 + lc) = ra[i];
; #pragma unroll
;     for (int i = 0; i < 2 * NI; ++i) {
;       *(u32x4*)(B0s + (lr + 32 * i) * 72 + lc) = rb0[i];
;       if (NB == 2) *(u32x4*)(B1s + (lr + 32 * i) * 72 + lc) = rb1[i];
;     }
;     ...
;     __syncthreads();
;     __builtin_amdgcn_s_setprio(1);
; #pragma unroll
;     for (int ks = 0; ks < 4; ++ks) {
;       bf16x8 af[2], bf0[NI], bf1[NI];
; #pragma unroll
;       for (int mi = 0; mi < 2; ++mi) af[mi] = *(const bf16x8*)(As + (64 * wm + 32 * mi + l31) * 72 + 16 * ks + 8 * h2);
; #pragma unroll
;       for (int ni = 0; ni < NI; ++ni) {
;         bf0[ni] = *(const bf16x8*)(B0s + (32 * NI * wn + 32 * ni + l31) * 72 + 16 * ks + 8 * h2);
;         if (NB == 2) bf1[ni] = *(const bf16x8*)(B1s + (32 * NI * wn + 32 * ni + l31) * 72 + 16 * ks + 8 * h2);
;       }
; #pragma unroll
;       for (int mi = 0; mi < 2; ++mi)
; #pragma unroll
;         for (int ni = 0; ni < NI; ++ni) {
;           acc0[mi][ni] = SWAP ? MFMA32(bf0[ni], af[mi], acc0[mi][ni]) : MFMA32(af[mi], bf0[ni], acc0[mi][ni]);
;           if (NB == 2) acc1[mi][ni] = SWAP ? MFMA32(bf1[ni], af[mi], acc1[mi][ni]) : MFMA32(af[mi], bf1[ni], acc1[mi][ni]);
;         }
;     }
	s_setprio 1
	ds_read_b128 v[200:203], v165 offset:18432
	ds_read_b128 v[204:207], v164
	ds_read_b128 v[220:223], v165 offset:23040
	s_waitcnt lgkmcnt(1)
	v_mfma_f32_32x32x16_bf16 v[50:65], v[200:203], v[204:207], v[50:65]
	s_waitcnt lgkmcnt(0)
	v_mfma_f32_32x32x16_bf16 v[34:49], v[220:223], v[204:207], v[34:49]
	ds_read_b128 v[204:207], v164 offset:4608
	s_waitcnt lgkmcnt(0)
	v_mfma_f32_32x32x16_bf16 v[18:33], v[200:203], v[204:207], v[18:33]
	v_mfma_f32_32x32x16_bf16 v[2:17], v[220:223], v[204:207], v[2:17]
	ds_read_b128 v[200:203], v165 offset:18464
	ds_read_b128 v[204:207], v164 offset:32
	ds_read_b128 v[220:223], v165 offset:23072
	s_waitcnt lgkmcnt(1)
	v_mfma_f32_32x32x16_bf16 v[50:65], v[200:203], v[204:207], v[50:65]
	s_waitcnt lgkmcnt(0)
	v_mfma_f32_32x32x16_bf16 v[34:49], v[220:223], v[204:207], v[34:49]
	ds_read_b128 v[204:207], v164 offset:4640
	s_waitcnt lgkmcnt(0)
	v_mfma_f32_32x32x16_bf16 v[18:33], v[200:203], v[204:207], v[18:33]
	v_mfma_f32_32x32x16_bf16 v[2:17], v[220:223], v[204:207], v[2:17]
	ds_read_b128 v[200:203], v165 offset:18496
	ds_read_b128 v[204:207], v164 offset:64
	ds_read_b128 v[220:223], v165 offset:23104
	s_waitcnt lgkmcnt(1)
	v_mfma_f32_32x32x16_bf16 v[50:65], v[200:203], v[204:207], v[50:65]
	s_waitcnt lgkmcnt(0)
	v_mfma_f32_32x32x16_bf16 v[34:49], v[220:223], v[204:207], v[34:49]
	ds_read_b128 v[204:207], v164 offset:4672
	s_waitcnt lgkmcnt(0)
	v_mfma_f32_32x32x16_bf16 v[18:33], v[200:203], v[204:207], v[18:33]
	v_mfma_f32_32x32x16_bf16 v[2:17], v[220:223], v[204:207], v[2:17]
	ds_read_b128 v[200:203], v165 offset:18528
	ds_read_b128 v[204:207], v164 offset:96
	ds_read_b128 v[220:223], v165 offset:23136
	s_waitcnt lgkmcnt(1)
	v_mfma_f32_32x32x16_bf16 v[50:65], v[200:203], v[204:207], v[50:65]
	s_waitcnt lgkmcnt(0)
	v_mfma_f32_32x32x16_bf16 v[34:49], v[220:223], v[204:207], v[34:49]
	ds_read_b128 v[204:207], v164 offset:4704
	s_waitcnt lgkmcnt(0)
	v_mfma_f32_32x32x16_bf16 v[18:33], v[200:203], v[204:207], v[18:33]
	v_mfma_f32_32x32x16_bf16 v[2:17], v[220:223], v[204:207], v[2:17]
	s_setprio 0
	s_barrier
	s_waitcnt vmcnt(7)
	ds_write_b128 v199, v[66:69]
	s_waitcnt vmcnt(5)
	ds_write_b128 v199, v[70:73] offset:4608
	s_waitcnt vmcnt(4)
	ds_write_b128 v199, v[74:77] offset:9216
	s_waitcnt vmcnt(3)
	ds_write_b128 v199, v[78:81] offset:13824
	s_waitcnt vmcnt(0)
	ds_write_b128 v199, v[94:97] offset:18432
	ds_write_b128 v199, v[90:93] offset:23040
	ds_write_b128 v199, v[86:89] offset:27648
	ds_write_b128 v199, v[82:85] offset:32256
	s_waitcnt lgkmcnt(0)
	s_barrier
; #define MFMA32(a, b, c) __builtin_amdgcn_mfma_f32_32x32x16_bf16((a), (b), (c), 0, 0, 0)
; template <int NI, int NB, bool SWAP = false>
; DI void gemm_main(f32x16 (&acc0)[2][NI], f32x16 (&acc1)[2][NI], const bf16_t* __restrict__ A, int lda,
;                   const bf16_t* __restrict__ B0, const bf16_t* __restrict__ B1, int ldb, int K, char* lds) {
;     ...
;     for (int ks = 0; ks < 4; ++ks) {
;       bf16x8 af[2], bf0[NI], bf1[NI];
; #pragma unroll
;       for (int mi = 0; mi < 2; ++mi) af[mi] = *(const bf16x8*)(As + (64 * wm + 32 * mi + l31) * 72 + 16 * ks + 8 * h2);
; #pragma unroll
;       for (int ni = 0; ni < NI; ++ni) {
;         bf0[ni] = *(const bf16x8*)(B0s + (32 * NI * wn + 32 * ni + l31) * 72 + 16 * ks + 8 * h2);
;         if (NB == 2) bf1[ni] = *(const bf16x8*)(B1s + (32 * NI * wn + 32 * ni + l31) * 72 + 16 * ks + 8 * h2);
;       }
; #pragma unroll
;       for (int mi = 0; mi < 2; ++mi)
; #pragma unroll
;         for (int ni = 0; ni < NI; ++ni) {
;           acc0[mi][ni] = SWAP ? MFMA32(bf0[ni], af[mi], acc0[mi][ni]) : MFMA32(af[mi], bf0[ni], acc0[mi][ni]);
;           if (NB == 2) acc1[mi][ni] = SWAP ? MFMA32(bf1[ni], af[mi], acc1[mi][ni]) : MFMA32(af[mi], bf1[ni], acc1[mi][ni]);
;         }
;     }
; DI void phase_merge(const bf16_t* __restrict__ Np, const bf16_t* __restrict__ Y, const bf16_t* __restrict__ WG,
;                             const bf16_t* __restrict__ WB, bf16_t* __restrict__ M, char* lds) {
;     ...
; #pragma unroll
;       for (int mi = 0; mi < 2; ++mi)
; #pragma unroll
;         for (int ni = 0; ni < 2; ++ni)
; #pragma unroll
;           for (int r = 0; r < 8; ++r) {
;             am[mi][ni][2 * r] += __uint_as_float(sg[mi][ni][r] << 16) * ab[mi][ni][2 * r];
;             am[mi][ni][2 * r + 1] += __uint_as_float(sg[mi][ni][r] & 0xffff0000u) * ab[mi][ni][2 * r + 1];
;           }
	s_setprio 1
	ds_read_b128 v[66:69], v165 offset:18432
	ds_read_b128 v[70:73], v164
	ds_read_b128 v[74:77], v165 offset:23040
	s_waitcnt lgkmcnt(1)
	v_mfma_f32_32x32x16_bf16 v[50:65], v[66:69], v[70:73], v[50:65]
	s_waitcnt lgkmcnt(0)
	v_mfma_f32_32x32x16_bf16 v[34:49], v[74:77], v[70:73], v[34:49]
	ds_read_b128 v[70:73], v164 offset:4608
	s_waitcnt lgkmcnt(0)
	v_mfma_f32_32x32x16_bf16 v[18:33], v[66:69], v[70:73], v[18:33]
	v_mfma_f32_32x32x16_bf16 v[2:17], v[74:77], v[70:73], v[2:17]
	ds_read_b128 v[66:69], v165 offset:18464
	ds_read_b128 v[70:73], v164 offset:32
	ds_read_b128 v[74:77], v165 offset:23072
	s_waitcnt lgkmcnt(1)
	v_mfma_f32_32x32x16_bf16 v[50:65], v[66:69], v[70:73], v[50:65]
	s_waitcnt lgkmcnt(0)
	v_mfma_f32_32x32x16_bf16 v[34:49], v[74:77], v[70:73], v[34:49]
	ds_read_b128 v[70:73], v164 offset:4640
	s_waitcnt lgkmcnt(0)
	v_mfma_f32_32x32x16_bf16 v[18:33], v[66:69], v[70:73], v[18:33]
	v_mfma_f32_32x32x16_bf16 v[2:17], v[74:77], v[70:73], v[2:17]
	ds_read_b128 v[66:69], v165 offset:18496
	ds_read_b128 v[70:73], v164 offset:64
	ds_read_b128 v[74:77], v165 offset:23104
	s_waitcnt lgkmcnt(1)
	v_mfma_f32_32x32x16_bf16 v[50:65], v[66:69], v[70:73], v[50:65]
	s_waitcnt lgkmcnt(0)
	v_mfma_f32_32x32x16_bf16 v[34:49], v[74:77], v[70:73], v[34:49]
	ds_read_b128 v[70:73], v164 offset:4672
	s_waitcnt lgkmcnt(0)
	v_mfma_f32_32x32x16_bf16 v[18:33], v[66:69], v[70:73], v[18:33]
	v_mfma_f32_32x32x16_bf16 v[2:17], v[74:77], v[70:73], v[2:17]
	ds_read_b128 v[66:69], v165 offset:18528
	ds_read_b128 v[70:73], v164 offset:96
	ds_read_b128 v[74:77], v165 offset:23136
	s_waitcnt lgkmcnt(1)
	v_mfma_f32_32x32x16_bf16 v[50:65], v[66:69], v[70:73], v[50:65]
	s_waitcnt lgkmcnt(0)
	v_mfma_f32_32x32x16_bf16 v[34:49], v[74:77], v[70:73], v[34:49]
	ds_read_b128 v[70:73], v164 offset:4704
	s_waitcnt lgkmcnt(0)
	v_mfma_f32_32x32x16_bf16 v[18:33], v[66:69], v[70:73], v[18:33]
	v_mfma_f32_32x32x16_bf16 v[2:17], v[74:77], v[70:73], v[2:17]
	s_setprio 0
	v_lshlrev_b32_e32 v66, 16, v167
	v_and_b32_e32 v67, 0xffff0000, v167
	s_nop 2
	v_fma_f32 v160, v50, v66, v160
	v_fma_f32 v161, v51, v67, v161
	v_lshlrev_b32_e32 v50, 16, v168
	v_and_b32_e32 v51, 0xffff0000, v168
	v_pk_fma_f32 v[162:163], v[52:53], v[50:51], v[162:163]
	v_lshlrev_b32_e32 v50, 16, v169
	v_and_b32_e32 v51, 0xffff0000, v169
	v_pk_fma_f32 v[156:157], v[54:55], v[50:51], v[156:157]
	v_lshlrev_b32_e32 v50, 16, v170
	v_and_b32_e32 v51, 0xffff0000, v170
	v_pk_fma_f32 v[158:159], v[56:57], v[50:51], v[158:159]
	v_lshlrev_b32_e32 v50, 16, v171
	v_and_b32_e32 v51, 0xffff0000, v171
	v_pk_fma_f32 v[152:153], v[58:59], v[50:51], v[152:153]
	v_lshlrev_b32_e32 v50, 16, v172
	v_and_b32_e32 v51, 0xffff0000, v172
	v_pk_fma_f32 v[154:155], v[60:61], v[50:51], v[154:155]
	v_lshlrev_b32_e32 v50, 16, v173
	v_and_b32_e32 v51, 0xffff0000, v173
	v_pk_fma_f32 v[150:151], v[62:63], v[50:51], v[150:151]
	v_lshlrev_b32_e32 v50, 16, v174
	v_and_b32_e32 v51, 0xffff0000, v174
	v_pk_fma_f32 v[118:119], v[64:65], v[50:51], v[118:119]
	v_lshlrev_b32_e32 v50, 16, v175
	v_and_b32_e32 v51, 0xffff0000, v175
	v_pk_fma_f32 v[146:147], v[34:35], v[50:51], v[146:147]
	v_lshlrev_b32_e32 v34, 16, v176
	v_and_b32_e32 v35, 0xffff0000, v176
	v_pk_fma_f32 v[148:149], v[36:37], v[34:35], v[148:149]
	v_lshlrev_b32_e32 v34, 16, v177
	v_and_b32_e32 v35, 0xffff0000, v177
	v_pk_fma_f32 v[142:143], v[38:39], v[34:35], v[142:143]
	v_lshlrev_b32_e32 v34, 16, v178
	v_and_b32_e32 v35, 0xffff0000, v178
	v_pk_fma_f32 v[144:145], v[40:41], v[34:35], v[144:145]
	v_lshlrev_b32_e32 v34, 16, v179
	v_and_b32_e32 v35, 0xffff0000, v179
	v_pk_fma_f32 v[138:139], v[42:43], v[34:35], v[138:139]
	v_lshlrev_b32_e32 v34, 16, v180
	v_and_b32_e32 v35, 0xffff0000, v180
	v_pk_fma_f32 v[140:141], v[44:45], v[34:35], v[140:141]
	v_lshlrev_b32_e32 v34, 16, v181
	v_and_b32_e32 v35, 0xffff0000, v181
	v_pk_fma_f32 v[136:137], v[46:47], v[34:35], v[136:137]
	v_lshlrev_b32_e32 v34, 16, v182
	v_and_b32_e32 v35, 0xffff0000, v182
	v_pk_fma_f32 v[104:105], v[48:49], v[34:35], v[104:105]
	v_lshlrev_b32_e32 v34, 16, v183
	v_and_b32_e32 v35, 0xffff0000, v183
	v_pk_fma_f32 v[132:133], v[18:19], v[34:35], v[132:133]
	v_lshlrev_b32_e32 v18, 16, v184
	v_and_b32_e32 v19, 0xffff0000, v184
	v_pk_fma_f32 v[134:135], v[20:21], v[18:19], v[134:135]
	v_lshlrev_b32_e32 v18, 16, v185
	v_and_b32_e32 v19, 0xffff0000, v185
	v_pk_fma_f32 v[128:129], v[22:23], v[18:19], v[128:129]
	v_lshlrev_b32_e32 v18, 16, v186
	v_and_b32_e32 v19, 0xffff0000, v186
	v_pk_fma_f32 v[130:131], v[24:25], v[18:19], v[130:131]
	v_lshlrev_b32_e32 v18, 16, v187
	v_and_b32_e32 v19, 0xffff0000, v187
	v_pk_fma_f32 v[124:125], v[26:27], v[18:19], v[124:125]
	v_lshlrev_b32_e32 v18, 16, v188
	v_and_b32_e32 v19, 0xffff0000, v188
	v_pk_fma_f32 v[126:127], v[28:29], v[18:19], v[126:127]
	v_lshlrev_b32_e32 v18, 16, v189
	v_and_b32_e32 v19, 0xffff0000, v189
	v_pk_fma_f32 v[122:123], v[30:31], v[18:19], v[122:123]
	v_lshlrev_b32_e32 v18, 16, v190
	v_and_b32_e32 v19, 0xffff0000, v190
	v_pk_fma_f32 v[102:103], v[32:33], v[18:19], v[102:103]
	v_lshlrev_b32_e32 v18, 16, v191
	v_and_b32_e32 v19, 0xffff0000, v191
	v_pk_fma_f32 v[116:117], v[2:3], v[18:19], v[116:117]
	v_lshlrev_b32_e32 v2, 16, v192
	v_and_b32_e32 v3, 0xffff0000, v192
	v_pk_fma_f32 v[120:121], v[4:5], v[2:3], v[120:121]
	v_lshlrev_b32_e32 v2, 16, v193
	v_and_b32_e32 v3, 0xffff0000, v193
	v_pk_fma_f32 v[112:113], v[6:7], v[2:3], v[112:113]
	v_lshlrev_b32_e32 v2, 16, v194
	v_and_b32_e32 v3, 0xffff0000, v194
	v_pk_fma_f32 v[114:115], v[8:9], v[2:3], v[114:115]
	v_lshlrev_b32_e32 v2, 16, v195
	v_and_b32_e32 v3, 0xffff0000, v195
	v_pk_fma_f32 v[108:109], v[10:11], v[2:3], v[108:109]
	v_lshlrev_b32_e32 v2, 16, v196
	v_and_b32_e32 v3, 0xffff0000, v196
	v_pk_fma_f32 v[110:111], v[12:13], v[2:3], v[110:111]
	v_lshlrev_b32_e32 v2, 16, v197
	v_and_b32_e32 v3, 0xffff0000, v197
	v_pk_fma_f32 v[106:107], v[14:15], v[2:3], v[106:107]
	v_lshlrev_b32_e32 v2, 16, v198
	v_and_b32_e32 v3, 0xffff0000, v198
	s_add_i32 s28, s28, 1
	s_cmp_eq_u32 s28, 4
	v_pk_fma_f32 v[100:101], v[16:17], v[2:3], v[100:101]
	s_cbranch_scc1 .LBB0_958
